# EpiAct epilogue: pair the two 8-byte output stores of each row group into one 16-byte store
# baseline (speedup 1.0000x reference)
;     __device__ __forceinline__ void operator()(f32x4 (&acc)[2][2][4][2], const Unit& u, int wr, int wc, int fr_in, int fq_in) const {
;     ...
;             for (int m = 0; m < 4; ++m) { const int row = row0 + ai * HALF + m * 16; const f32x4 pv = *(const f32x4*)(ss + (size_t)row * 16 + 4 * fq); float sq = (pv[0] + pv[1]) + (pv[2] + pv[3]); sq += __shfl_xor(sq, 16); sq += __shfl_xor(sq, 32); const float rs = rsqrtf(sq * (1.0f / 1024.0f) + 1e-6f);
; #pragma unroll
;                 for (int bj = 0; bj < 2; ++bj)
; #pragma unroll
;                     for (int n = 0; n < 2; ++n) acc[ai][bj][m][n] = acc[ai][bj][m][n] * rs; }
;         if (fr >= 14) {
; #pragma unroll
;             for (int ai = 0; ai < 2; ++ai) { PG8_LAS float* x = xl + ((((wave * 2 + ai) * 2 + (fr - 14)) * 4 + fq) * 8); *(PG8_LAS f32x4*)x = acc[ai][0][3][0]; *(PG8_LAS f32x4*)(x + 4) = acc[ai][0][3][1]; }
;             if (wr == 1) { float* s = sb + ((size_t)(0 * 128 + u.pm) * 2 + (fr - 14)) * 2816 + cb; *(f32x4*)s = acc[1][0][3][0]; *(f32x4*)(s + 4) = acc[1][0][3][1]; } }
;         if (wr == 0 && fr < 2) { float* s = sb + ((size_t)(1 * 128 + u.pm) * 2 + fr) * 2816 + cb; *(f32x4*)s = acc[0][0][0][0]; *(f32x4*)(s + 4) = acc[0][0][0][1];
;             float* t = sb + ((size_t)(2 * 128 + u.pm) * 2 + fr) * 2816 + cb; *(f32x4*)t = acc[0][1][0][0]; *(f32x4*)(t + 4) = acc[0][1][0][1]; }
;         asm volatile("s_waitcnt lgkmcnt(0)" ::: "memory"); __builtin_amdgcn_s_barrier(); asm volatile("" ::: "memory");
; #pragma unroll
;         for (int ai = 0; ai < 2; ++ai)
; #pragma unroll
;             for (int m = 0; m < 4; ++m) {
;                 const bool skip = (ai == 0) && (m == 0) && (wr == 0) && (fr < 2);
;                 bf16_t* op = O + (size_t)(row0 + ai * HALF + m * 16) * 2816 + cb;
; #pragma unroll
;                 for (int n = 0; n < 2; ++n) { f32x4 p1, p2;
;                     if (m == 0) { const int sai = (wr == 1) ? ai : (ai > 0 ? ai - 1 : 0); const int swave = (wr ^ 1) * 4 + wc;
;                         p1 = *(const PG8_LAS f32x4*)(xl + ((((swave * 2 + sai) * 2 + 1) * 4 + fq) * 8) + 4 * n); p2 = *(const PG8_LAS f32x4*)(xl + ((((swave * 2 + sai) * 2 + (fr == 0 ? 0 : 1)) * 4 + fq) * 8) + 4 * n); }
; #pragma unroll
;                     for (int e = 0; e < 4; ++e) { const float gv = acc[ai][0][m][n][e]; const float s1 = dpp_ror<0x121>(gv), s2 = dpp_ror<0x122>(gv); float q1, q2;
.LBB0_535:
	s_or_b64 exec, exec, s[0:1]
	v_mov_b64_e32 v[152:153], v[116:117]
	v_mov_b64_e32 v[154:155], v[118:119]
	v_mov_b64_e32 v[220:221], v[112:113]
	v_mov_b64_e32 v[222:223], v[114:115]
	v_mov_b64_e32 v[230:231], v[120:121]
	v_mov_b64_e32 v[232:233], v[122:123]
	v_mul_f32_e32 v160, 0x4b800000, v210
	v_mov_b32_dpp v187, v148 row_ror:1 row_mask:0xf bank_mask:0xf
	v_mov_b32_dpp v191, v148 row_ror:2 row_mask:0xf bank_mask:0xf
	v_cndmask_b32_e64 v148, v210, v160, s[12:13]
	v_mov_b32_dpp v214, v150 row_ror:1 row_mask:0xf bank_mask:0xf
	v_mov_b32_dpp v234, v150 row_ror:2 row_mask:0xf bank_mask:0xf
	v_rsq_f32_e32 v150, v148
	v_mov_b64_e32 v[156:157], s[28:29]
	s_movk_i32 s0, 0x2000
	s_movk_i32 s33, 0x1600
	v_lshlrev_b64 v[158:159], 1, v[208:209]
	v_mov_b32_dpp v193, v149 row_ror:1 row_mask:0xf bank_mask:0xf
	v_mov_b32_dpp v205, v149 row_ror:2 row_mask:0xf bank_mask:0xf
	v_add_co_u32_e32 v208, vcc, s0, v198
	v_mad_i64_i32 v[148:149], s[0:1], v206, s33, v[156:157]
	v_lshl_add_u64 v[210:211], v[148:149], 0, v[158:159]
	v_mul_f32_e32 v148, 0x45800000, v150
	v_cndmask_b32_e64 v160, v150, v148, s[12:13]
	v_mov_b32_dpp v236, v151 row_ror:1 row_mask:0xf bank_mask:0xf
	v_mov_b32_dpp v235, v151 row_ror:2 row_mask:0xf bank_mask:0xf
	v_pk_mul_f32 v[148:149], v[110:111], v[160:161] op_sel_hi:[1,0]
	v_pk_mul_f32 v[150:151], v[108:109], v[160:161] op_sel_hi:[1,0]
	v_addc_co_u32_e32 v209, vcc, 0, v199, vcc
	s_nop 0
	v_mov_b32_dpp v238, v150 row_ror:1 row_mask:0xf bank_mask:0xf
	v_mov_b32_dpp v240, v151 row_ror:1 row_mask:0xf bank_mask:0xf
	v_mov_b32_dpp v242, v148 row_ror:1 row_mask:0xf bank_mask:0xf
	v_mov_b32_dpp v244, v149 row_ror:1 row_mask:0xf bank_mask:0xf
	v_mov_b32_dpp v239, v150 row_ror:2 row_mask:0xf bank_mask:0xf
	v_mov_b32_dpp v241, v151 row_ror:2 row_mask:0xf bank_mask:0xf
	v_mov_b32_dpp v243, v148 row_ror:2 row_mask:0xf bank_mask:0xf
	v_mov_b32_dpp v245, v149 row_ror:2 row_mask:0xf bank_mask:0xf
	v_cndmask_b32_e64 v207, v193, v240, s[14:15]
	v_cndmask_b32_e64 v206, v187, v238, s[68:69]
	v_cndmask_b32_e64 v237, v236, v244, s[14:15]
	v_cndmask_b32_e64 v236, v214, v242, s[68:69]
	v_cndmask_b32_e64 v213, v205, v241, s[64:65]
	v_cndmask_b32_e64 v212, v191, v239, s[66:67]
	v_cndmask_b32_e64 v235, v235, v245, s[64:65]
	v_cndmask_b32_e64 v234, v234, v243, s[66:67]
	s_movk_i32 s0, 0x5000
	v_mov_b32_dpp v187, v144 row_ror:1 row_mask:0xf bank_mask:0xf
	v_mov_b32_dpp v191, v144 row_ror:2 row_mask:0xf bank_mask:0xf
	v_mov_b32_dpp v193, v145 row_ror:1 row_mask:0xf bank_mask:0xf
	v_mov_b32_dpp v205, v145 row_ror:2 row_mask:0xf bank_mask:0xf
	v_mov_b32_dpp v214, v146 row_ror:1 row_mask:0xf bank_mask:0xf
	v_pk_mul_f32 v[144:145], v[106:107], v[160:161] op_sel_hi:[1,0]
	s_mov_b32 s71, 0x800000
	v_pk_mul_f32 v[152:153], v[152:153], v[206:207]
	v_pk_mul_f32 v[154:155], v[154:155], v[236:237]
	v_pk_fma_f32 v[152:153], v[220:221], v[212:213], v[152:153]
	v_pk_fma_f32 v[154:155], v[222:223], v[234:235], v[154:155]
	v_pk_fma_f32 v[150:151], v[150:151], v[230:231], v[152:153]
	v_pk_fma_f32 v[148:149], v[148:149], v[232:233], v[154:155]
	v_mul_f32_e32 v152, 0xbfb8aa3b, v150
	v_mul_f32_e32 v153, 0xbfb8aa3b, v151
	v_mul_f32_e32 v154, 0xbfb8aa3b, v148
	v_mul_f32_e32 v155, 0xbfb8aa3b, v149
	v_exp_f32_e32 v152, v152
	v_exp_f32_e32 v153, v153
	v_exp_f32_e32 v154, v154
	v_exp_f32_e32 v155, v155
	v_add_f32_e32 v152, 1.0, v152
	v_add_f32_e32 v153, 1.0, v153
	v_add_f32_e32 v154, 1.0, v154
	v_add_f32_e32 v155, 1.0, v155
	v_rcp_f32_e32 v152, v152
	v_rcp_f32_e32 v153, v153
	v_rcp_f32_e32 v154, v154
	v_rcp_f32_e32 v155, v155
	v_pk_mul_f32 v[206:207], v[102:103], v[160:161] op_sel_hi:[1,0]
	v_pk_mul_f32 v[212:213], v[100:101], v[160:161] op_sel_hi:[1,0]
	v_pk_mul_f32 v[150:151], v[150:151], v[152:153]
	v_pk_mul_f32 v[148:149], v[148:149], v[154:155]
	v_pk_mul_f32 v[150:151], v[212:213], v[150:151]
	v_pk_mul_f32 v[148:149], v[206:207], v[148:149]
	v_cvt_pk_bf16_f32 v150, v150, v151
	v_cvt_pk_bf16_f32 v151, v148, v149
	v_mov_b64_e32 v[12:13], v[150:151]
	v_mov_b64_e32 v[148:149], v[124:125]
	v_mov_b64_e32 v[150:151], v[126:127]
	v_mov_b64_e32 v[152:153], v[72:73]
	v_mov_b64_e32 v[154:155], v[74:75]
	v_add_co_u32_e32 v206, vcc, s0, v198
	v_mov_b32_dpp v232, v146 row_ror:2 row_mask:0xf bank_mask:0xf
	s_nop 0
	v_addc_co_u32_e32 v207, vcc, 0, v199, vcc
	v_mov_b64_e32 v[220:221], v[76:77]
	v_mov_b64_e32 v[222:223], v[78:79]
	v_mov_b32_dpp v234, v147 row_ror:1 row_mask:0xf bank_mask:0xf
	v_mov_b32_dpp v233, v147 row_ror:2 row_mask:0xf bank_mask:0xf
	v_pk_mul_f32 v[146:147], v[104:105], v[160:161] op_sel_hi:[1,0]
	v_mov_b32_dpp v248, v144 row_ror:1 row_mask:0xf bank_mask:0xf
	v_mov_b32_dpp v215, v145 row_ror:1 row_mask:0xf bank_mask:0xf
	v_mov_b32_dpp v236, v146 row_ror:1 row_mask:0xf bank_mask:0xf
	v_mov_b32_dpp v246, v147 row_ror:1 row_mask:0xf bank_mask:0xf
	v_mov_b32_dpp v237, v146 row_ror:2 row_mask:0xf bank_mask:0xf
	v_mov_b32_dpp v247, v147 row_ror:2 row_mask:0xf bank_mask:0xf
	v_mov_b32_dpp v249, v144 row_ror:2 row_mask:0xf bank_mask:0xf
	v_mov_b32_dpp v251, v145 row_ror:2 row_mask:0xf bank_mask:0xf
	v_cndmask_b32_e64 v213, v193, v246, s[14:15]
	v_cndmask_b32_e64 v212, v187, v236, s[68:69]
	v_cndmask_b32_e64 v235, v234, v215, s[14:15]
	v_cndmask_b32_e64 v234, v214, v248, s[68:69]
	v_cndmask_b32_e64 v231, v205, v247, s[64:65]
	v_cndmask_b32_e64 v230, v191, v237, s[66:67]
	v_cndmask_b32_e64 v233, v233, v251, s[64:65]
	v_cndmask_b32_e64 v232, v232, v249, s[66:67]
	v_mad_i64_i32 v[204:205], s[0:1], v204, s33, v[156:157]
	v_lshl_add_u64 v[204:205], v[204:205], 0, v[158:159]
	v_pk_mul_f32 v[152:153], v[152:153], v[212:213]
	v_pk_mul_f32 v[154:155], v[154:155], v[234:235]
; #define PG8_LAS __attribute__((address_space(3)))
; __device__ __forceinline__ unsigned cvt_pk_bf16(float lo, float hi) { typedef float f2 __attribute__((ext_vector_type(2))); typedef __bf16 b2 __attribute__((ext_vector_type(2))); f2 v = {lo, hi}; b2 b = __builtin_convertvector(v, b2); return __builtin_bit_cast(unsigned, b); }
; template <int CTRL> __device__ __forceinline__ float dpp_ror(float v) { return __builtin_bit_cast(float, __builtin_amdgcn_mov_dpp(__builtin_bit_cast(int, v), CTRL, 0xf, 0xf, false)); }
;     __device__ __forceinline__ void operator()(f32x4 (&acc)[2][2][4][2], const Unit& u, int wr, int wc, int fr_in, int fq_in) const {
;     ...
;                 for (int n = 0; n < 2; ++n) { f32x4 p1, p2;
;                     if (m == 0) { const int sai = (wr == 1) ? ai : (ai > 0 ? ai - 1 : 0); const int swave = (wr ^ 1) * 4 + wc;
;                         p1 = *(const PG8_LAS f32x4*)(xl + ((((swave * 2 + sai) * 2 + 1) * 4 + fq) * 8) + 4 * n); p2 = *(const PG8_LAS f32x4*)(xl + ((((swave * 2 + sai) * 2 + (fr == 0 ? 0 : 1)) * 4 + fq) * 8) + 4 * n); }
; #pragma unroll
;                     for (int e = 0; e < 4; ++e) { const float gv = acc[ai][0][m][n][e]; const float s1 = dpp_ror<0x121>(gv), s2 = dpp_ror<0x122>(gv); float q1, q2;
;                         if (m > 0) { const float pvv = acc[ai][0][m > 0 ? m - 1 : 0][n][e]; q1 = dpp_ror<0x121>(pvv); q2 = dpp_ror<0x122>(pvv); } else { q1 = p1[e]; q2 = p2[e]; }
;                         p1[e] = fr >= 1 ? s1 : q1; p2[e] = fr >= 2 ? s2 : q2; }
;                     const f32x4 w0 = *(const f32x4*)(cw + cb + 4 * n), w1 = *(const f32x4*)(cw + 2816 + cb + 4 * n), w2 = *(const f32x4*)(cw + 2 * 2816 + cb + 4 * n);
;                     const f32x4 cv = w0 * p2 + w1 * p1 + w2 * acc[ai][0][m][n]; f32x4 o;
; #pragma unroll
;                     for (int e = 0; e < 4; ++e) o[e] = cv[e] * __builtin_amdgcn_rcpf(1.0f + __builtin_amdgcn_exp2f(-1.4426950408889634f * cv[e])) * acc[ai][1][m][n][e];
;                     typedef unsigned u32x2_ __attribute__((ext_vector_type(2))); u32x2_ wv; wv.x = cvt_pk_bf16(o[0], o[1]); wv.y = cvt_pk_bf16(o[2], o[3]);
;                     if (!skip) *(u32x2_*)(op + 4 * n) = wv;
;                     asm volatile("" ::: "memory"); } }
	v_pk_fma_f32 v[148:149], v[148:149], v[230:231], v[152:153]
	v_pk_fma_f32 v[150:151], v[150:151], v[232:233], v[154:155]
	v_pk_mul_f32 v[152:153], v[98:99], v[160:161] op_sel_hi:[1,0]
	v_pk_mul_f32 v[154:155], v[96:97], v[160:161] op_sel_hi:[1,0]
	v_pk_fma_f32 v[146:147], v[146:147], v[220:221], v[148:149]
	v_pk_fma_f32 v[144:145], v[144:145], v[222:223], v[150:151]
	v_mul_f32_e32 v148, 0xbfb8aa3b, v146
	v_mul_f32_e32 v149, 0xbfb8aa3b, v147
	v_mul_f32_e32 v150, 0xbfb8aa3b, v144
	v_mul_f32_e32 v151, 0xbfb8aa3b, v145
	v_exp_f32_e32 v148, v148
	v_exp_f32_e32 v149, v149
	v_exp_f32_e32 v150, v150
	v_exp_f32_e32 v151, v151
	v_add_f32_e32 v148, 1.0, v148
	v_add_f32_e32 v149, 1.0, v149
	v_add_f32_e32 v150, 1.0, v150
	v_add_f32_e32 v151, 1.0, v151
	v_rcp_f32_e32 v148, v148
	v_rcp_f32_e32 v149, v149
	v_rcp_f32_e32 v150, v150
	v_rcp_f32_e32 v151, v151
	v_mul_f32_e32 v160, 0x4b800000, v189
	v_pk_mul_f32 v[146:147], v[146:147], v[148:149]
	v_cndmask_b32_e64 v160, v189, v160, s[10:11]
	v_pk_mul_f32 v[144:145], v[144:145], v[150:151]
	v_pk_mul_f32 v[146:147], v[154:155], v[146:147]
	v_pk_mul_f32 v[144:145], v[152:153], v[144:145]
	v_cvt_pk_bf16_f32 v146, v146, v147
	v_cvt_pk_bf16_f32 v147, v144, v145
	v_mov_b64_e32 v[14:15], v[146:147]
	global_store_dwordx4 v[210:211], v[12:15], off
	v_mov_b64_e32 v[144:145], v[116:117]
	v_mov_b64_e32 v[146:147], v[118:119]
	v_mov_b64_e32 v[148:149], v[112:113]
	v_mov_b64_e32 v[150:151], v[114:115]
	v_mov_b64_e32 v[152:153], v[120:121]
	v_mov_b64_e32 v[154:155], v[122:123]
	v_rsq_f32_e32 v160, v160
	v_mov_b32_e32 v189, v188
	v_mul_f32_e32 v187, 0x45800000, v160
	v_cndmask_b32_e64 v160, v160, v187, s[10:11]
	v_pk_mul_f32 v[210:211], v[94:95], v[160:161] op_sel_hi:[1,0]
	v_pk_mul_f32 v[212:213], v[92:93], v[160:161] op_sel_hi:[1,0]
	s_mov_b32 s10, 0x800000
	v_mov_b32_dpp v234, v210 row_ror:1 row_mask:0xf bank_mask:0xf
	v_mov_b32_dpp v187, v212 row_ror:1 row_mask:0xf bank_mask:0xf
	v_mov_b32_dpp v193, v213 row_ror:1 row_mask:0xf bank_mask:0xf
	v_mov_b32_dpp v252, v211 row_ror:1 row_mask:0xf bank_mask:0xf
	v_mov_b32_dpp v191, v212 row_ror:2 row_mask:0xf bank_mask:0xf
	v_mov_b32_dpp v214, v213 row_ror:2 row_mask:0xf bank_mask:0xf
	v_mov_b32_dpp v235, v210 row_ror:2 row_mask:0xf bank_mask:0xf
	v_mov_b32_dpp v250, v211 row_ror:2 row_mask:0xf bank_mask:0xf
	v_cndmask_b32_e64 v221, v240, v193, s[14:15]
	v_cndmask_b32_e64 v220, v238, v187, s[68:69]
	v_cndmask_b32_e64 v233, v244, v252, s[14:15]
	v_cndmask_b32_e64 v232, v242, v234, s[68:69]
	v_cndmask_b32_e64 v223, v241, v214, s[64:65]
	v_cndmask_b32_e64 v222, v239, v191, s[66:67]
	v_cndmask_b32_e64 v231, v245, v250, s[64:65]
	v_cndmask_b32_e64 v230, v243, v235, s[66:67]
	v_pk_mul_f32 v[144:145], v[144:145], v[220:221]
	v_pk_mul_f32 v[146:147], v[146:147], v[232:233]
	v_pk_fma_f32 v[144:145], v[148:149], v[222:223], v[144:145]
	v_pk_fma_f32 v[146:147], v[150:151], v[230:231], v[146:147]
	v_pk_fma_f32 v[144:145], v[212:213], v[152:153], v[144:145]
	v_pk_fma_f32 v[146:147], v[210:211], v[154:155], v[146:147]
	v_mul_f32_e32 v148, 0xbfb8aa3b, v144
	v_mul_f32_e32 v149, 0xbfb8aa3b, v145
	v_mul_f32_e32 v150, 0xbfb8aa3b, v146
	v_mul_f32_e32 v151, 0xbfb8aa3b, v147
	v_exp_f32_e32 v148, v148
	v_exp_f32_e32 v149, v149
	v_exp_f32_e32 v150, v150
	v_exp_f32_e32 v151, v151
	v_add_f32_e32 v148, 1.0, v148
	v_add_f32_e32 v149, 1.0, v149
	v_add_f32_e32 v150, 1.0, v150
	v_add_f32_e32 v151, 1.0, v151
	v_rcp_f32_e32 v148, v148
	v_rcp_f32_e32 v149, v149
	v_rcp_f32_e32 v150, v150
	v_rcp_f32_e32 v151, v151
	v_pk_mul_f32 v[152:153], v[86:87], v[160:161] op_sel_hi:[1,0]
	v_pk_mul_f32 v[154:155], v[84:85], v[160:161] op_sel_hi:[1,0]
	v_pk_mul_f32 v[144:145], v[144:145], v[148:149]
	v_pk_mul_f32 v[146:147], v[146:147], v[150:151]
	v_pk_mul_f32 v[144:145], v[154:155], v[144:145]
	v_pk_mul_f32 v[146:147], v[152:153], v[146:147]
	v_cvt_pk_bf16_f32 v144, v144, v145
	v_cvt_pk_bf16_f32 v145, v146, v147
	v_mov_b64_e32 v[12:13], v[144:145]
	v_mov_b64_e32 v[144:145], v[72:73]
	v_mov_b64_e32 v[146:147], v[74:75]
	v_mov_b64_e32 v[148:149], v[124:125]
	v_mov_b64_e32 v[150:151], v[126:127]
	v_mov_b64_e32 v[152:153], v[76:77]
	v_mov_b64_e32 v[154:155], v[78:79]
	v_pk_mul_f32 v[210:211], v[90:91], v[160:161] op_sel_hi:[1,0]
	v_pk_mul_f32 v[212:213], v[88:89], v[160:161] op_sel_hi:[1,0]
	s_nop 0
	v_mov_b32_dpp v242, v210 row_ror:1 row_mask:0xf bank_mask:0xf
	v_mov_b32_dpp v238, v212 row_ror:1 row_mask:0xf bank_mask:0xf
	v_mov_b32_dpp v240, v213 row_ror:1 row_mask:0xf bank_mask:0xf
	v_mov_b32_dpp v244, v211 row_ror:1 row_mask:0xf bank_mask:0xf
	v_mov_b32_dpp v239, v212 row_ror:2 row_mask:0xf bank_mask:0xf
	v_mov_b32_dpp v241, v213 row_ror:2 row_mask:0xf bank_mask:0xf
	v_mov_b32_dpp v243, v210 row_ror:2 row_mask:0xf bank_mask:0xf
	v_mov_b32_dpp v245, v211 row_ror:2 row_mask:0xf bank_mask:0xf
	v_cndmask_b32_e64 v221, v246, v240, s[14:15]
	v_cndmask_b32_e64 v220, v236, v238, s[68:69]
	v_cndmask_b32_e64 v233, v215, v244, s[14:15]
	v_cndmask_b32_e64 v232, v248, v242, s[68:69]
	v_cndmask_b32_e64 v223, v247, v241, s[64:65]
	v_cndmask_b32_e64 v222, v237, v239, s[66:67]
	v_cndmask_b32_e64 v231, v251, v245, s[64:65]
	v_cndmask_b32_e64 v230, v249, v243, s[66:67]
	v_mov_b32_dpp v215, v140 row_ror:2 row_mask:0xf bank_mask:0xf
	v_pk_mul_f32 v[144:145], v[144:145], v[220:221]
	v_pk_mul_f32 v[146:147], v[146:147], v[232:233]
	v_pk_fma_f32 v[144:145], v[148:149], v[222:223], v[144:145]
	v_pk_fma_f32 v[146:147], v[150:151], v[230:231], v[146:147]
	v_pk_fma_f32 v[144:145], v[212:213], v[152:153], v[144:145]
	v_pk_fma_f32 v[146:147], v[210:211], v[154:155], v[146:147]
	v_mul_f32_e32 v148, 0xbfb8aa3b, v144
	v_mul_f32_e32 v149, 0xbfb8aa3b, v145
; #define PG8_LAS __attribute__((address_space(3)))
; __device__ __forceinline__ unsigned cvt_pk_bf16(float lo, float hi) { typedef float f2 __attribute__((ext_vector_type(2))); typedef __bf16 b2 __attribute__((ext_vector_type(2))); f2 v = {lo, hi}; b2 b = __builtin_convertvector(v, b2); return __builtin_bit_cast(unsigned, b); }
; template <int CTRL> __device__ __forceinline__ float dpp_ror(float v) { return __builtin_bit_cast(float, __builtin_amdgcn_mov_dpp(__builtin_bit_cast(int, v), CTRL, 0xf, 0xf, false)); }
;     __device__ __forceinline__ void operator()(f32x4 (&acc)[2][2][4][2], const Unit& u, int wr, int wc, int fr_in, int fq_in) const {
;     ...
;                 for (int n = 0; n < 2; ++n) { f32x4 p1, p2;
;                     if (m == 0) { const int sai = (wr == 1) ? ai : (ai > 0 ? ai - 1 : 0); const int swave = (wr ^ 1) * 4 + wc;
;                         p1 = *(const PG8_LAS f32x4*)(xl + ((((swave * 2 + sai) * 2 + 1) * 4 + fq) * 8) + 4 * n); p2 = *(const PG8_LAS f32x4*)(xl + ((((swave * 2 + sai) * 2 + (fr == 0 ? 0 : 1)) * 4 + fq) * 8) + 4 * n); }
; #pragma unroll
;                     for (int e = 0; e < 4; ++e) { const float gv = acc[ai][0][m][n][e]; const float s1 = dpp_ror<0x121>(gv), s2 = dpp_ror<0x122>(gv); float q1, q2;
;                         if (m > 0) { const float pvv = acc[ai][0][m > 0 ? m - 1 : 0][n][e]; q1 = dpp_ror<0x121>(pvv); q2 = dpp_ror<0x122>(pvv); } else { q1 = p1[e]; q2 = p2[e]; }
;                         p1[e] = fr >= 1 ? s1 : q1; p2[e] = fr >= 2 ? s2 : q2; }
;                     const f32x4 w0 = *(const f32x4*)(cw + cb + 4 * n), w1 = *(const f32x4*)(cw + 2816 + cb + 4 * n), w2 = *(const f32x4*)(cw + 2 * 2816 + cb + 4 * n);
;                     const f32x4 cv = w0 * p2 + w1 * p1 + w2 * acc[ai][0][m][n]; f32x4 o;
; #pragma unroll
;                     for (int e = 0; e < 4; ++e) o[e] = cv[e] * __builtin_amdgcn_rcpf(1.0f + __builtin_amdgcn_exp2f(-1.4426950408889634f * cv[e])) * acc[ai][1][m][n][e];
;                     typedef unsigned u32x2_ __attribute__((ext_vector_type(2))); u32x2_ wv; wv.x = cvt_pk_bf16(o[0], o[1]); wv.y = cvt_pk_bf16(o[2], o[3]);
;                     if (!skip) *(u32x2_*)(op + 4 * n) = wv;
;                     asm volatile("" ::: "memory"); } }
	v_mul_f32_e32 v150, 0xbfb8aa3b, v146
	v_mul_f32_e32 v151, 0xbfb8aa3b, v147
	v_exp_f32_e32 v148, v148
	v_exp_f32_e32 v149, v149
	v_exp_f32_e32 v150, v150
	v_exp_f32_e32 v151, v151
	v_add_f32_e32 v148, 1.0, v148
	v_add_f32_e32 v149, 1.0, v149
	v_add_f32_e32 v150, 1.0, v150
	v_add_f32_e32 v151, 1.0, v151
	v_rcp_f32_e32 v148, v148
	v_rcp_f32_e32 v149, v149
	v_rcp_f32_e32 v150, v150
	v_rcp_f32_e32 v151, v151
	v_pk_mul_f32 v[152:153], v[82:83], v[160:161] op_sel_hi:[1,0]
	v_pk_mul_f32 v[154:155], v[80:81], v[160:161] op_sel_hi:[1,0]
	v_pk_mul_f32 v[144:145], v[144:145], v[148:149]
	v_pk_mul_f32 v[146:147], v[146:147], v[150:151]
	v_pk_mul_f32 v[144:145], v[154:155], v[144:145]
	v_pk_mul_f32 v[146:147], v[152:153], v[146:147]
	v_cvt_pk_bf16_f32 v144, v144, v145
	v_cvt_pk_bf16_f32 v145, v146, v147
	v_mov_b64_e32 v[14:15], v[144:145]
	global_store_dwordx4 v[204:205], v[12:15], off
	v_mov_b64_e32 v[144:145], v[116:117]
	v_mov_b64_e32 v[146:147], v[118:119]
	v_mov_b64_e32 v[148:149], v[112:113]
	v_mov_b64_e32 v[150:151], v[114:115]
	v_mov_b64_e32 v[152:153], v[120:121]
	v_mov_b64_e32 v[154:155], v[122:123]
	v_mov_b32_dpp v160, v140 row_ror:1 row_mask:0xf bank_mask:0xf
	v_mov_b32_dpp v220, v141 row_ror:1 row_mask:0xf bank_mask:0xf
	v_mov_b32_dpp v232, v142 row_ror:1 row_mask:0xf bank_mask:0xf
	v_mov_b32_dpp v233, v143 row_ror:1 row_mask:0xf bank_mask:0xf
	v_mov_b32_dpp v222, v141 row_ror:2 row_mask:0xf bank_mask:0xf
	v_mov_b32_dpp v230, v142 row_ror:2 row_mask:0xf bank_mask:0xf
	v_mov_b32_dpp v231, v143 row_ror:2 row_mask:0xf bank_mask:0xf
	v_cndmask_b32_e64 v221, v193, v220, s[14:15]
	v_cndmask_b32_e64 v220, v187, v160, s[68:69]
	v_cndmask_b32_e64 v233, v252, v233, s[14:15]
	v_cndmask_b32_e64 v232, v234, v232, s[68:69]
	v_cndmask_b32_e64 v223, v214, v222, s[64:65]
	v_cndmask_b32_e64 v222, v191, v215, s[66:67]
	v_cndmask_b32_e64 v231, v250, v231, s[64:65]
	v_cndmask_b32_e64 v230, v235, v230, s[66:67]
	v_mov_b32_e32 v204, v188
	v_mov_b32_e32 v205, v188
	v_pk_mul_f32 v[210:211], v[70:71], v[204:205]
	v_pk_mul_f32 v[212:213], v[68:69], v[188:189]
	v_mov_b32_dpp v193, v138 row_ror:1 row_mask:0xf bank_mask:0xf
	v_mov_b32_dpp v160, v136 row_ror:2 row_mask:0xf bank_mask:0xf
	v_mov_b32_dpp v187, v137 row_ror:2 row_mask:0xf bank_mask:0xf
	v_cndmask_b32_e64 v191, v241, v187, s[64:65]
	v_pk_mul_f32 v[144:145], v[144:145], v[220:221]
	v_pk_mul_f32 v[146:147], v[146:147], v[232:233]
	v_pk_fma_f32 v[144:145], v[148:149], v[222:223], v[144:145]
	v_pk_fma_f32 v[146:147], v[150:151], v[230:231], v[146:147]
	v_pk_fma_f32 v[140:141], v[140:141], v[152:153], v[144:145]
	v_pk_fma_f32 v[142:143], v[142:143], v[154:155], v[146:147]
	v_mul_f32_e32 v144, 0xbfb8aa3b, v140
	v_mul_f32_e32 v145, 0xbfb8aa3b, v141
	v_mul_f32_e32 v146, 0xbfb8aa3b, v142
	v_mul_f32_e32 v147, 0xbfb8aa3b, v143
	v_exp_f32_e32 v144, v144
	v_exp_f32_e32 v145, v145
	v_exp_f32_e32 v146, v146
	v_exp_f32_e32 v147, v147
	v_add_f32_e32 v144, 1.0, v144
	v_add_f32_e32 v145, 1.0, v145
	v_add_f32_e32 v146, 1.0, v146
	v_add_f32_e32 v147, 1.0, v147
	v_rcp_f32_e32 v144, v144
	v_rcp_f32_e32 v145, v145
	v_rcp_f32_e32 v146, v146
	v_rcp_f32_e32 v147, v147
	v_mad_i64_i32 v[148:149], s[0:1], v190, s33, v[156:157]
	v_pk_mul_f32 v[140:141], v[140:141], v[144:145]
	v_pk_mul_f32 v[142:143], v[142:143], v[146:147]
	v_pk_mul_f32 v[140:141], v[212:213], v[140:141]
	v_pk_mul_f32 v[142:143], v[210:211], v[142:143]
	v_lshl_add_u64 v[152:153], v[148:149], 0, v[158:159]
	v_cvt_pk_bf16_f32 v140, v140, v141
	v_cvt_pk_bf16_f32 v141, v142, v143
	v_mov_b64_e32 v[12:13], v[140:141]
	v_mov_b64_e32 v[140:141], v[72:73]
	v_mov_b64_e32 v[142:143], v[74:75]
	v_mov_b64_e32 v[144:145], v[124:125]
	v_mov_b64_e32 v[146:147], v[126:127]
	v_mov_b64_e32 v[148:149], v[76:77]
	v_mov_b64_e32 v[150:151], v[78:79]
	v_mov_b32_dpp v154, v136 row_ror:1 row_mask:0xf bank_mask:0xf
	v_mov_b32_dpp v155, v137 row_ror:1 row_mask:0xf bank_mask:0xf
	v_mov_b32_dpp v212, v139 row_ror:1 row_mask:0xf bank_mask:0xf
	v_mov_b32_dpp v210, v138 row_ror:2 row_mask:0xf bank_mask:0xf
	v_mov_b32_dpp v211, v139 row_ror:2 row_mask:0xf bank_mask:0xf
	v_cndmask_b32_e64 v155, v240, v155, s[14:15]
	v_cndmask_b32_e64 v154, v238, v154, s[68:69]
	v_cndmask_b32_e64 v213, v244, v212, s[14:15]
	v_cndmask_b32_e64 v212, v242, v193, s[68:69]
	v_cndmask_b32_e64 v190, v239, v160, s[66:67]
	v_cndmask_b32_e64 v211, v245, v211, s[64:65]
	v_cndmask_b32_e64 v210, v243, v210, s[66:67]
	v_readlane_b32 s0, v254, 52
	v_pk_mul_f32 v[140:141], v[140:141], v[154:155]
	v_pk_mul_f32 v[142:143], v[142:143], v[212:213]
	v_pk_fma_f32 v[140:141], v[144:145], v[190:191], v[140:141]
	v_pk_fma_f32 v[142:143], v[146:147], v[210:211], v[142:143]
	v_pk_fma_f32 v[136:137], v[136:137], v[148:149], v[140:141]
	v_pk_fma_f32 v[138:139], v[138:139], v[150:151], v[142:143]
	v_mul_f32_e32 v140, 0xbfb8aa3b, v136
	v_mul_f32_e32 v141, 0xbfb8aa3b, v137
	v_mul_f32_e32 v142, 0xbfb8aa3b, v138
	v_mul_f32_e32 v143, 0xbfb8aa3b, v139
	v_exp_f32_e32 v140, v140
	v_exp_f32_e32 v141, v141
	v_exp_f32_e32 v142, v142
	v_exp_f32_e32 v143, v143
	v_add_f32_e32 v140, 1.0, v140
	v_add_f32_e32 v141, 1.0, v141
	v_add_f32_e32 v142, 1.0, v142
	v_add_f32_e32 v143, 1.0, v143
	v_rcp_f32_e32 v140, v140
	v_rcp_f32_e32 v141, v141
	v_rcp_f32_e32 v142, v142
	v_rcp_f32_e32 v143, v143
	v_pk_mul_f32 v[144:145], v[66:67], v[204:205]
	v_pk_mul_f32 v[146:147], v[64:65], v[188:189]
	v_pk_mul_f32 v[136:137], v[136:137], v[140:141]
	v_pk_mul_f32 v[138:139], v[138:139], v[142:143]
	v_pk_mul_f32 v[136:137], v[146:147], v[136:137]
	v_pk_mul_f32 v[138:139], v[144:145], v[138:139]
	v_cvt_pk_bf16_f32 v136, v136, v137
	v_cvt_pk_bf16_f32 v137, v138, v139
	v_mov_b64_e32 v[14:15], v[136:137]
;     __device__ __forceinline__ void operator()(f32x4 (&acc)[2][2][4][2], const Unit& u, int wr, int wc, int fr_in, int fq_in) const {
;     ...
;             for (int m = 0; m < 4; ++m) { const int row = row0 + ai * HALF + m * 16; const f32x4 pv = *(const f32x4*)(ss + (size_t)row * 16 + 4 * fq); float sq = (pv[0] + pv[1]) + (pv[2] + pv[3]); sq += __shfl_xor(sq, 16); sq += __shfl_xor(sq, 32); const float rs = rsqrtf(sq * (1.0f / 1024.0f) + 1e-6f);
; #pragma unroll
;                 for (int bj = 0; bj < 2; ++bj)
; #pragma unroll
;                     for (int n = 0; n < 2; ++n) acc[ai][bj][m][n] = acc[ai][bj][m][n] * rs; }
;         if (fr >= 14) {
; #pragma unroll
;             for (int ai = 0; ai < 2; ++ai) { PG8_LAS float* x = xl + ((((wave * 2 + ai) * 2 + (fr - 14)) * 4 + fq) * 8); *(PG8_LAS f32x4*)x = acc[ai][0][3][0]; *(PG8_LAS f32x4*)(x + 4) = acc[ai][0][3][1]; }
;             if (wr == 1) { float* s = sb + ((size_t)(0 * 128 + u.pm) * 2 + (fr - 14)) * 2816 + cb; *(f32x4*)s = acc[1][0][3][0]; *(f32x4*)(s + 4) = acc[1][0][3][1]; } }
;         if (wr == 0 && fr < 2) { float* s = sb + ((size_t)(1 * 128 + u.pm) * 2 + fr) * 2816 + cb; *(f32x4*)s = acc[0][0][0][0]; *(f32x4*)(s + 4) = acc[0][0][0][1];
;             float* t = sb + ((size_t)(2 * 128 + u.pm) * 2 + fr) * 2816 + cb; *(f32x4*)t = acc[0][1][0][0]; *(f32x4*)(t + 4) = acc[0][1][0][1]; }
;         asm volatile("s_waitcnt lgkmcnt(0)" ::: "memory"); __builtin_amdgcn_s_barrier(); asm volatile("" ::: "memory");
; #pragma unroll
;         for (int ai = 0; ai < 2; ++ai)
; #pragma unroll
;             for (int m = 0; m < 4; ++m) {
;                 const bool skip = (ai == 0) && (m == 0) && (wr == 0) && (fr < 2);
;                 bf16_t* op = O + (size_t)(row0 + ai * HALF + m * 16) * 2816 + cb;
; #pragma unroll
;                 for (int n = 0; n < 2; ++n) { f32x4 p1, p2;
;                     if (m == 0) { const int sai = (wr == 1) ? ai : (ai > 0 ? ai - 1 : 0); const int swave = (wr ^ 1) * 4 + wc;
;                         p1 = *(const PG8_LAS f32x4*)(xl + ((((swave * 2 + sai) * 2 + 1) * 4 + fq) * 8) + 4 * n); p2 = *(const PG8_LAS f32x4*)(xl + ((((swave * 2 + sai) * 2 + (fr == 0 ? 0 : 1)) * 4 + fq) * 8) + 4 * n); }
; #pragma unroll
;                     for (int e = 0; e < 4; ++e) { const float gv = acc[ai][0][m][n][e]; const float s1 = dpp_ror<0x121>(gv), s2 = dpp_ror<0x122>(gv); float q1, q2;
	global_store_dwordx4 v[152:153], v[12:15], off
	v_mov_b64_e32 v[136:137], v[116:117]
	v_mov_b64_e32 v[138:139], v[118:119]
	v_mov_b64_e32 v[140:141], v[112:113]
	v_mov_b64_e32 v[142:143], v[114:115]
	v_mov_b64_e32 v[144:145], v[120:121]
	v_mov_b64_e32 v[146:147], v[122:123]
	v_pk_add_f32 v[148:149], v[194:195], v[196:197]
	v_or_b32_e32 v150, s93, v183
	v_pk_fma_f32 v[188:189], v[148:149], s[80:81], v[162:163] op_sel_hi:[1,0,0]
	v_add_u32_e32 v183, s0, v181
	v_mul_f32_e32 v148, 0x4b800000, v189
	v_cmp_gt_f32_e32 vcc, s10, v189
	v_lshlrev_b32_e32 v150, 7, v150
	v_add3_u32 v181, s51, v150, v181
	v_cndmask_b32_e32 v148, v189, v148, vcc
	v_rsq_f32_e32 v151, v148
	v_mad_i64_i32 v[148:149], s[0:1], v192, s33, v[156:157]
	v_lshl_add_u64 v[190:191], v[148:149], 0, v[158:159]
	v_mul_f32_e32 v148, 0x45800000, v151
	v_cndmask_b32_e32 v160, v151, v148, vcc
	ds_read_b128 v[148:151], v183 offset:128
	ds_read_b128 v[152:155], v181
	v_pk_mul_f32 v[192:193], v[62:63], v[160:161] op_sel_hi:[1,0]
	v_pk_mul_f32 v[194:195], v[60:61], v[160:161] op_sel_hi:[1,0]
	v_cmp_gt_f32_e32 vcc, s10, v188
	v_mov_b32_dpp v204, v192 row_ror:1 row_mask:0xf bank_mask:0xf
	v_mov_b32_dpp v189, v194 row_ror:1 row_mask:0xf bank_mask:0xf
	v_mov_b32_dpp v187, v195 row_ror:1 row_mask:0xf bank_mask:0xf
	v_mov_b32_dpp v210, v193 row_ror:1 row_mask:0xf bank_mask:0xf
	v_mov_b32_dpp v196, v194 row_ror:2 row_mask:0xf bank_mask:0xf
	v_mov_b32_dpp v197, v195 row_ror:2 row_mask:0xf bank_mask:0xf
	v_mov_b32_dpp v205, v192 row_ror:2 row_mask:0xf bank_mask:0xf
	v_mov_b32_dpp v211, v193 row_ror:2 row_mask:0xf bank_mask:0xf
	s_waitcnt lgkmcnt(1)
	v_cndmask_b32_e64 v149, v149, v187, s[14:15]
	v_cndmask_b32_e64 v148, v148, v189, s[68:69]
	v_cndmask_b32_e64 v151, v151, v210, s[14:15]
	v_cndmask_b32_e64 v150, v150, v204, s[68:69]
	s_waitcnt lgkmcnt(0)
	v_cndmask_b32_e64 v153, v153, v197, s[64:65]
	v_cndmask_b32_e64 v152, v152, v196, s[66:67]
	v_cndmask_b32_e64 v155, v155, v211, s[64:65]
	v_cndmask_b32_e64 v154, v154, v205, s[66:67]
	v_pk_mul_f32 v[136:137], v[148:149], v[136:137]
	v_pk_mul_f32 v[138:139], v[150:151], v[138:139]
	v_pk_fma_f32 v[136:137], v[152:153], v[140:141], v[136:137]
	v_pk_fma_f32 v[138:139], v[154:155], v[142:143], v[138:139]
	v_pk_fma_f32 v[136:137], v[194:195], v[144:145], v[136:137]
	v_pk_fma_f32 v[138:139], v[192:193], v[146:147], v[138:139]
	v_mul_f32_e32 v140, 0xbfb8aa3b, v136
	v_mul_f32_e32 v141, 0xbfb8aa3b, v137
	v_mul_f32_e32 v142, 0xbfb8aa3b, v138
	v_mul_f32_e32 v143, 0xbfb8aa3b, v139
	v_exp_f32_e32 v140, v140
	v_exp_f32_e32 v141, v141
	v_exp_f32_e32 v142, v142
	v_exp_f32_e32 v143, v143
	v_add_f32_e32 v140, 1.0, v140
	v_add_f32_e32 v141, 1.0, v141
	v_add_f32_e32 v142, 1.0, v142
	v_add_f32_e32 v143, 1.0, v143
	v_rcp_f32_e32 v140, v140
	v_rcp_f32_e32 v141, v141
	v_rcp_f32_e32 v142, v142
	v_rcp_f32_e32 v143, v143
	v_pk_mul_f32 v[144:145], v[54:55], v[160:161] op_sel_hi:[1,0]
	v_pk_mul_f32 v[146:147], v[52:53], v[160:161] op_sel_hi:[1,0]
	v_pk_mul_f32 v[136:137], v[136:137], v[140:141]
	v_pk_mul_f32 v[138:139], v[138:139], v[142:143]
	v_pk_mul_f32 v[136:137], v[146:147], v[136:137]
	v_pk_mul_f32 v[138:139], v[144:145], v[138:139]
	v_cvt_pk_bf16_f32 v136, v136, v137
	v_cvt_pk_bf16_f32 v137, v138, v139
	v_mov_b64_e32 v[12:13], v[136:137]
	v_mov_b64_e32 v[136:137], v[72:73]
	v_mov_b64_e32 v[138:139], v[74:75]
	v_mov_b64_e32 v[140:141], v[124:125]
	v_mov_b64_e32 v[142:143], v[126:127]
	v_mov_b64_e32 v[144:145], v[76:77]
	v_mov_b64_e32 v[146:147], v[78:79]
	ds_read_b128 v[148:151], v183 offset:144
	ds_read_b128 v[152:155], v181 offset:16
	v_pk_mul_f32 v[192:193], v[58:59], v[160:161] op_sel_hi:[1,0]
	v_pk_mul_f32 v[194:195], v[56:57], v[160:161] op_sel_hi:[1,0]
	s_nop 0
	v_mov_b32_dpp v220, v192 row_ror:1 row_mask:0xf bank_mask:0xf
	v_mov_b32_dpp v212, v194 row_ror:1 row_mask:0xf bank_mask:0xf
	v_mov_b32_dpp v214, v195 row_ror:1 row_mask:0xf bank_mask:0xf
	v_mov_b32_dpp v181, v193 row_ror:1 row_mask:0xf bank_mask:0xf
	v_mov_b32_dpp v213, v194 row_ror:2 row_mask:0xf bank_mask:0xf
	v_mov_b32_dpp v215, v195 row_ror:2 row_mask:0xf bank_mask:0xf
	v_mov_b32_dpp v183, v192 row_ror:2 row_mask:0xf bank_mask:0xf
	v_mov_b32_dpp v221, v193 row_ror:2 row_mask:0xf bank_mask:0xf
	s_waitcnt lgkmcnt(1)
	v_cndmask_b32_e64 v149, v149, v214, s[14:15]
	v_cndmask_b32_e64 v148, v148, v212, s[68:69]
	v_cndmask_b32_e64 v151, v151, v181, s[14:15]
	v_cndmask_b32_e64 v150, v150, v220, s[68:69]
	s_waitcnt lgkmcnt(0)
;     __device__ __forceinline__ void operator()(f32x4 (&acc)[2][2][4][2], const Unit& u, int wr, int wc, int fr_in, int fq_in) const {
;     ...
;             for (int m = 0; m < 4; ++m) { const int row = row0 + ai * HALF + m * 16; const f32x4 pv = *(const f32x4*)(ss + (size_t)row * 16 + 4 * fq); float sq = (pv[0] + pv[1]) + (pv[2] + pv[3]); sq += __shfl_xor(sq, 16); sq += __shfl_xor(sq, 32); const float rs = rsqrtf(sq * (1.0f / 1024.0f) + 1e-6f);
; #pragma unroll
;                 for (int bj = 0; bj < 2; ++bj)
; #pragma unroll
;                     for (int n = 0; n < 2; ++n) acc[ai][bj][m][n] = acc[ai][bj][m][n] * rs; }
;         if (fr >= 14) {
; #pragma unroll
;             for (int ai = 0; ai < 2; ++ai) { PG8_LAS float* x = xl + ((((wave * 2 + ai) * 2 + (fr - 14)) * 4 + fq) * 8); *(PG8_LAS f32x4*)x = acc[ai][0][3][0]; *(PG8_LAS f32x4*)(x + 4) = acc[ai][0][3][1]; }
;             if (wr == 1) { float* s = sb + ((size_t)(0 * 128 + u.pm) * 2 + (fr - 14)) * 2816 + cb; *(f32x4*)s = acc[1][0][3][0]; *(f32x4*)(s + 4) = acc[1][0][3][1]; } }
;         if (wr == 0 && fr < 2) { float* s = sb + ((size_t)(1 * 128 + u.pm) * 2 + fr) * 2816 + cb; *(f32x4*)s = acc[0][0][0][0]; *(f32x4*)(s + 4) = acc[0][0][0][1];
;             float* t = sb + ((size_t)(2 * 128 + u.pm) * 2 + fr) * 2816 + cb; *(f32x4*)t = acc[0][1][0][0]; *(f32x4*)(t + 4) = acc[0][1][0][1]; }
;         asm volatile("s_waitcnt lgkmcnt(0)" ::: "memory"); __builtin_amdgcn_s_barrier(); asm volatile("" ::: "memory");
; #pragma unroll
;         for (int ai = 0; ai < 2; ++ai)
; #pragma unroll
;             for (int m = 0; m < 4; ++m) {
;                 const bool skip = (ai == 0) && (m == 0) && (wr == 0) && (fr < 2);
;                 bf16_t* op = O + (size_t)(row0 + ai * HALF + m * 16) * 2816 + cb;
; #pragma unroll
;                 for (int n = 0; n < 2; ++n) { f32x4 p1, p2;
;                     if (m == 0) { const int sai = (wr == 1) ? ai : (ai > 0 ? ai - 1 : 0); const int swave = (wr ^ 1) * 4 + wc;
;                         p1 = *(const PG8_LAS f32x4*)(xl + ((((swave * 2 + sai) * 2 + 1) * 4 + fq) * 8) + 4 * n); p2 = *(const PG8_LAS f32x4*)(xl + ((((swave * 2 + sai) * 2 + (fr == 0 ? 0 : 1)) * 4 + fq) * 8) + 4 * n); }
; #pragma unroll
;                     for (int e = 0; e < 4; ++e) { const float gv = acc[ai][0][m][n][e]; const float s1 = dpp_ror<0x121>(gv), s2 = dpp_ror<0x122>(gv); float q1, q2;
	v_cndmask_b32_e64 v153, v153, v215, s[64:65]
	v_cndmask_b32_e64 v152, v152, v213, s[66:67]
	v_cndmask_b32_e64 v155, v155, v221, s[64:65]
	v_cndmask_b32_e64 v154, v154, v183, s[66:67]
	v_pk_mul_f32 v[136:137], v[148:149], v[136:137]
	v_pk_mul_f32 v[138:139], v[150:151], v[138:139]
	v_pk_fma_f32 v[136:137], v[152:153], v[140:141], v[136:137]
	v_pk_fma_f32 v[138:139], v[154:155], v[142:143], v[138:139]
	v_pk_fma_f32 v[136:137], v[194:195], v[144:145], v[136:137]
	v_pk_fma_f32 v[138:139], v[192:193], v[146:147], v[138:139]
	v_mul_f32_e32 v140, 0xbfb8aa3b, v136
	v_mul_f32_e32 v141, 0xbfb8aa3b, v137
	v_mul_f32_e32 v142, 0xbfb8aa3b, v138
	v_mul_f32_e32 v143, 0xbfb8aa3b, v139
	v_exp_f32_e32 v140, v140
	v_exp_f32_e32 v141, v141
	v_exp_f32_e32 v142, v142
	v_exp_f32_e32 v143, v143
	v_add_f32_e32 v140, 1.0, v140
	v_add_f32_e32 v141, 1.0, v141
	v_add_f32_e32 v142, 1.0, v142
	v_add_f32_e32 v143, 1.0, v143
	v_rcp_f32_e32 v140, v140
	v_rcp_f32_e32 v141, v141
	v_rcp_f32_e32 v142, v142
	v_rcp_f32_e32 v143, v143
	v_pk_mul_f32 v[144:145], v[50:51], v[160:161] op_sel_hi:[1,0]
	v_pk_mul_f32 v[146:147], v[48:49], v[160:161] op_sel_hi:[1,0]
	v_pk_mul_f32 v[136:137], v[136:137], v[140:141]
	v_pk_mul_f32 v[138:139], v[138:139], v[142:143]
	v_pk_mul_f32 v[136:137], v[146:147], v[136:137]
	v_pk_mul_f32 v[138:139], v[144:145], v[138:139]
	v_cvt_pk_bf16_f32 v136, v136, v137
	v_cvt_pk_bf16_f32 v137, v138, v139
	v_mov_b64_e32 v[14:15], v[136:137]
	global_store_dwordx4 v[190:191], v[12:15], off
	v_mov_b64_e32 v[136:137], v[116:117]
	v_mov_b64_e32 v[138:139], v[118:119]
	v_mov_b64_e32 v[140:141], v[112:113]
	v_mov_b64_e32 v[142:143], v[114:115]
	v_mov_b64_e32 v[144:145], v[120:121]
	v_mov_b64_e32 v[146:147], v[122:123]
	v_mul_f32_e32 v148, 0x4b800000, v188
	v_cndmask_b32_e32 v148, v188, v148, vcc
	v_rsq_f32_e32 v150, v148
	v_mad_i64_i32 v[148:149], s[0:1], v186, s33, v[156:157]
	v_lshl_add_u64 v[148:149], v[148:149], 0, v[158:159]
	v_mul_f32_e32 v151, 0x45800000, v150
	v_cndmask_b32_e32 v150, v150, v151, vcc
	v_pk_mul_f32 v[152:153], v[46:47], v[150:151] op_sel_hi:[1,0]
	v_pk_mul_f32 v[154:155], v[44:45], v[150:151] op_sel_hi:[1,0]
	s_nop 0
	v_mov_b32_dpp v222, v152 row_ror:1 row_mask:0xf bank_mask:0xf
	v_mov_b32_dpp v151, v154 row_ror:1 row_mask:0xf bank_mask:0xf
	v_mov_b32_dpp v194, v155 row_ror:1 row_mask:0xf bank_mask:0xf
	v_mov_b32_dpp v230, v153 row_ror:1 row_mask:0xf bank_mask:0xf
	v_mov_b32_dpp v160, v154 row_ror:2 row_mask:0xf bank_mask:0xf
	v_mov_b32_dpp v195, v155 row_ror:2 row_mask:0xf bank_mask:0xf
	v_mov_b32_dpp v223, v152 row_ror:2 row_mask:0xf bank_mask:0xf
	v_mov_b32_dpp v231, v153 row_ror:2 row_mask:0xf bank_mask:0xf
	v_cndmask_b32_e64 v187, v187, v194, s[14:15]
	v_cndmask_b32_e64 v186, v189, v151, s[68:69]
	v_cndmask_b32_e64 v193, v210, v230, s[14:15]
	v_cndmask_b32_e64 v192, v204, v222, s[68:69]
	v_cndmask_b32_e64 v189, v197, v195, s[64:65]
	v_cndmask_b32_e64 v188, v196, v160, s[66:67]
	v_cndmask_b32_e64 v191, v211, v231, s[64:65]
	v_cndmask_b32_e64 v190, v205, v223, s[66:67]
	v_pk_mul_f32 v[136:137], v[136:137], v[186:187]
	v_pk_mul_f32 v[138:139], v[138:139], v[192:193]
	v_pk_fma_f32 v[136:137], v[140:141], v[188:189], v[136:137]
	v_pk_fma_f32 v[138:139], v[142:143], v[190:191], v[138:139]
	v_pk_fma_f32 v[136:137], v[154:155], v[144:145], v[136:137]
	v_pk_fma_f32 v[138:139], v[152:153], v[146:147], v[138:139]
	v_mul_f32_e32 v140, 0xbfb8aa3b, v136
	v_mul_f32_e32 v141, 0xbfb8aa3b, v137
	v_mul_f32_e32 v142, 0xbfb8aa3b, v138
	v_mul_f32_e32 v143, 0xbfb8aa3b, v139
	v_exp_f32_e32 v140, v140
	v_exp_f32_e32 v141, v141
	v_exp_f32_e32 v142, v142
	v_exp_f32_e32 v143, v143
	v_add_f32_e32 v140, 1.0, v140
	v_add_f32_e32 v141, 1.0, v141
	v_add_f32_e32 v142, 1.0, v142
	v_add_f32_e32 v143, 1.0, v143
	v_rcp_f32_e32 v140, v140
	v_rcp_f32_e32 v141, v141
	v_rcp_f32_e32 v142, v142
	v_rcp_f32_e32 v143, v143
	v_pk_mul_f32 v[144:145], v[38:39], v[150:151] op_sel_hi:[1,0]
	v_pk_mul_f32 v[146:147], v[36:37], v[150:151] op_sel_hi:[1,0]
	v_pk_mul_f32 v[136:137], v[136:137], v[140:141]
	v_pk_mul_f32 v[138:139], v[138:139], v[142:143]
	v_pk_mul_f32 v[136:137], v[146:147], v[136:137]
	v_pk_mul_f32 v[138:139], v[144:145], v[138:139]
	v_cvt_pk_bf16_f32 v136, v136, v137
	v_cvt_pk_bf16_f32 v137, v138, v139
	v_mov_b64_e32 v[12:13], v[136:137]
	v_mov_b64_e32 v[136:137], v[72:73]
	v_mov_b64_e32 v[138:139], v[74:75]
	v_mov_b64_e32 v[140:141], v[124:125]
	v_mov_b64_e32 v[142:143], v[126:127]
	v_mov_b64_e32 v[144:145], v[76:77]
	v_mov_b64_e32 v[146:147], v[78:79]
	v_pk_mul_f32 v[152:153], v[42:43], v[150:151] op_sel_hi:[1,0]
	v_pk_mul_f32 v[154:155], v[40:41], v[150:151] op_sel_hi:[1,0]
	s_nop 0
	v_mov_b32_dpp v210, v152 row_ror:1 row_mask:0xf bank_mask:0xf
	v_mov_b32_dpp v196, v154 row_ror:1 row_mask:0xf bank_mask:0xf
	v_mov_b32_dpp v204, v155 row_ror:1 row_mask:0xf bank_mask:0xf
	v_mov_b32_dpp v232, v153 row_ror:1 row_mask:0xf bank_mask:0xf
	v_mov_b32_dpp v197, v154 row_ror:2 row_mask:0xf bank_mask:0xf
	v_mov_b32_dpp v205, v155 row_ror:2 row_mask:0xf bank_mask:0xf
	v_mov_b32_dpp v211, v152 row_ror:2 row_mask:0xf bank_mask:0xf
	v_mov_b32_dpp v233, v153 row_ror:2 row_mask:0xf bank_mask:0xf
	v_cndmask_b32_e64 v187, v214, v204, s[14:15]
	v_cndmask_b32_e64 v186, v212, v196, s[68:69]
	v_cndmask_b32_e64 v193, v181, v232, s[14:15]
	v_cndmask_b32_e64 v192, v220, v210, s[68:69]
	v_cndmask_b32_e64 v189, v215, v205, s[64:65]
	v_cndmask_b32_e64 v188, v213, v197, s[66:67]
	v_cndmask_b32_e64 v191, v221, v233, s[64:65]
	v_cndmask_b32_e64 v190, v183, v211, s[66:67]
	v_pk_mul_f32 v[136:137], v[136:137], v[186:187]
	v_pk_mul_f32 v[138:139], v[138:139], v[192:193]
	v_pk_fma_f32 v[136:137], v[140:141], v[188:189], v[136:137]
; #define PG8_LAS __attribute__((address_space(3)))
; __device__ __forceinline__ unsigned cvt_pk_bf16(float lo, float hi) { typedef float f2 __attribute__((ext_vector_type(2))); typedef __bf16 b2 __attribute__((ext_vector_type(2))); f2 v = {lo, hi}; b2 b = __builtin_convertvector(v, b2); return __builtin_bit_cast(unsigned, b); }
; template <int CTRL> __device__ __forceinline__ float dpp_ror(float v) { return __builtin_bit_cast(float, __builtin_amdgcn_mov_dpp(__builtin_bit_cast(int, v), CTRL, 0xf, 0xf, false)); }
;     __device__ __forceinline__ void operator()(f32x4 (&acc)[2][2][4][2], const Unit& u, int wr, int wc, int fr_in, int fq_in) const {
;     ...
;                 for (int n = 0; n < 2; ++n) { f32x4 p1, p2;
;                     if (m == 0) { const int sai = (wr == 1) ? ai : (ai > 0 ? ai - 1 : 0); const int swave = (wr ^ 1) * 4 + wc;
;                         p1 = *(const PG8_LAS f32x4*)(xl + ((((swave * 2 + sai) * 2 + 1) * 4 + fq) * 8) + 4 * n); p2 = *(const PG8_LAS f32x4*)(xl + ((((swave * 2 + sai) * 2 + (fr == 0 ? 0 : 1)) * 4 + fq) * 8) + 4 * n); }
; #pragma unroll
;                     for (int e = 0; e < 4; ++e) { const float gv = acc[ai][0][m][n][e]; const float s1 = dpp_ror<0x121>(gv), s2 = dpp_ror<0x122>(gv); float q1, q2;
;                         if (m > 0) { const float pvv = acc[ai][0][m > 0 ? m - 1 : 0][n][e]; q1 = dpp_ror<0x121>(pvv); q2 = dpp_ror<0x122>(pvv); } else { q1 = p1[e]; q2 = p2[e]; }
;                         p1[e] = fr >= 1 ? s1 : q1; p2[e] = fr >= 2 ? s2 : q2; }
;                     const f32x4 w0 = *(const f32x4*)(cw + cb + 4 * n), w1 = *(const f32x4*)(cw + 2816 + cb + 4 * n), w2 = *(const f32x4*)(cw + 2 * 2816 + cb + 4 * n);
;                     const f32x4 cv = w0 * p2 + w1 * p1 + w2 * acc[ai][0][m][n]; f32x4 o;
; #pragma unroll
;                     for (int e = 0; e < 4; ++e) o[e] = cv[e] * __builtin_amdgcn_rcpf(1.0f + __builtin_amdgcn_exp2f(-1.4426950408889634f * cv[e])) * acc[ai][1][m][n][e];
;                     typedef unsigned u32x2_ __attribute__((ext_vector_type(2))); u32x2_ wv; wv.x = cvt_pk_bf16(o[0], o[1]); wv.y = cvt_pk_bf16(o[2], o[3]);
;                     if (!skip) *(u32x2_*)(op + 4 * n) = wv;
;                     asm volatile("" ::: "memory"); } }
	v_pk_fma_f32 v[138:139], v[142:143], v[190:191], v[138:139]
	v_pk_fma_f32 v[136:137], v[154:155], v[144:145], v[136:137]
	v_pk_fma_f32 v[138:139], v[152:153], v[146:147], v[138:139]
	v_mul_f32_e32 v140, 0xbfb8aa3b, v136
	v_mul_f32_e32 v141, 0xbfb8aa3b, v137
	v_mul_f32_e32 v142, 0xbfb8aa3b, v138
	v_mul_f32_e32 v143, 0xbfb8aa3b, v139
	v_exp_f32_e32 v140, v140
	v_exp_f32_e32 v141, v141
	v_exp_f32_e32 v142, v142
	v_exp_f32_e32 v143, v143
	v_add_f32_e32 v140, 1.0, v140
	v_add_f32_e32 v141, 1.0, v141
	v_add_f32_e32 v142, 1.0, v142
	v_add_f32_e32 v143, 1.0, v143
	v_rcp_f32_e32 v140, v140
	v_rcp_f32_e32 v141, v141
	v_rcp_f32_e32 v142, v142
	v_rcp_f32_e32 v143, v143
	v_pk_mul_f32 v[144:145], v[34:35], v[150:151] op_sel_hi:[1,0]
	v_pk_mul_f32 v[146:147], v[32:33], v[150:151] op_sel_hi:[1,0]
	v_pk_mul_f32 v[136:137], v[136:137], v[140:141]
	v_pk_mul_f32 v[138:139], v[138:139], v[142:143]
	v_pk_mul_f32 v[136:137], v[146:147], v[136:137]
	v_pk_mul_f32 v[138:139], v[144:145], v[138:139]
	v_cvt_pk_bf16_f32 v136, v136, v137
	v_cvt_pk_bf16_f32 v137, v138, v139
	v_mov_b64_e32 v[14:15], v[136:137]
	global_store_dwordx4 v[148:149], v[12:15], off
	v_mov_b64_e32 v[136:137], v[116:117]
	v_mov_b64_e32 v[138:139], v[118:119]
	v_mov_b64_e32 v[140:141], v[112:113]
	v_mov_b64_e32 v[142:143], v[114:115]
	v_mov_b64_e32 v[144:145], v[120:121]
	v_mov_b64_e32 v[146:147], v[122:123]
	v_mul_f32_e32 v148, 0x4b800000, v185
	v_cndmask_b32_e64 v148, v185, v148, s[8:9]
	v_rsq_f32_e32 v150, v148
	v_mad_i64_i32 v[148:149], s[0:1], v182, s33, v[156:157]
	v_lshl_add_u64 v[148:149], v[148:149], 0, v[158:159]
	v_mul_f32_e32 v152, 0x45800000, v150
	v_cndmask_b32_e64 v150, v150, v152, s[8:9]
	v_pk_mul_f32 v[152:153], v[30:31], v[150:151] op_sel_hi:[1,0]
	v_pk_mul_f32 v[154:155], v[28:29], v[150:151] op_sel_hi:[1,0]
	v_mov_b32_e32 v185, v184
	v_mov_b32_dpp v213, v152 row_ror:1 row_mask:0xf bank_mask:0xf
	v_mov_b32_dpp v181, v154 row_ror:1 row_mask:0xf bank_mask:0xf
	v_mov_b32_dpp v193, v155 row_ror:1 row_mask:0xf bank_mask:0xf
	v_mov_b32_dpp v215, v153 row_ror:1 row_mask:0xf bank_mask:0xf
	v_mov_b32_dpp v192, v154 row_ror:2 row_mask:0xf bank_mask:0xf
	v_mov_b32_dpp v212, v155 row_ror:2 row_mask:0xf bank_mask:0xf
	v_mov_b32_dpp v214, v152 row_ror:2 row_mask:0xf bank_mask:0xf
	v_mov_b32_dpp v220, v153 row_ror:2 row_mask:0xf bank_mask:0xf
	v_cndmask_b32_e64 v183, v194, v193, s[14:15]
	v_cndmask_b32_e64 v182, v151, v181, s[68:69]
	v_cndmask_b32_e64 v191, v230, v215, s[14:15]
	v_cndmask_b32_e64 v190, v222, v213, s[68:69]
	v_cndmask_b32_e64 v187, v195, v212, s[64:65]
	v_cndmask_b32_e64 v186, v160, v192, s[66:67]
	v_cndmask_b32_e64 v189, v231, v220, s[64:65]
	v_cndmask_b32_e64 v188, v223, v214, s[66:67]
	v_pk_mul_f32 v[136:137], v[136:137], v[182:183]
	v_pk_mul_f32 v[138:139], v[138:139], v[190:191]
	v_pk_fma_f32 v[136:137], v[140:141], v[186:187], v[136:137]
	v_pk_fma_f32 v[138:139], v[142:143], v[188:189], v[138:139]
	v_pk_fma_f32 v[136:137], v[154:155], v[144:145], v[136:137]
	v_pk_fma_f32 v[138:139], v[152:153], v[146:147], v[138:139]
	v_mul_f32_e32 v140, 0xbfb8aa3b, v136
	v_mul_f32_e32 v141, 0xbfb8aa3b, v137
	v_mul_f32_e32 v142, 0xbfb8aa3b, v138
	v_mul_f32_e32 v143, 0xbfb8aa3b, v139
	v_exp_f32_e32 v140, v140
	v_exp_f32_e32 v141, v141
	v_exp_f32_e32 v142, v142
	v_exp_f32_e32 v143, v143
	v_add_f32_e32 v140, 1.0, v140
	v_add_f32_e32 v141, 1.0, v141
	v_add_f32_e32 v142, 1.0, v142
	v_add_f32_e32 v143, 1.0, v143
	v_rcp_f32_e32 v140, v140
	v_rcp_f32_e32 v141, v141
	v_rcp_f32_e32 v142, v142
	v_rcp_f32_e32 v143, v143
	v_pk_mul_f32 v[144:145], v[22:23], v[150:151] op_sel_hi:[1,0]
	v_pk_mul_f32 v[146:147], v[20:21], v[150:151] op_sel_hi:[1,0]
	v_pk_mul_f32 v[136:137], v[136:137], v[140:141]
	v_pk_mul_f32 v[138:139], v[138:139], v[142:143]
	v_pk_mul_f32 v[136:137], v[146:147], v[136:137]
	v_pk_mul_f32 v[138:139], v[144:145], v[138:139]
	v_cvt_pk_bf16_f32 v136, v136, v137
	v_cvt_pk_bf16_f32 v137, v138, v139
	v_mov_b64_e32 v[12:13], v[136:137]
	v_mov_b64_e32 v[136:137], v[72:73]
	v_mov_b64_e32 v[138:139], v[74:75]
	v_mov_b64_e32 v[140:141], v[124:125]
	v_mov_b64_e32 v[142:143], v[126:127]
	v_mov_b64_e32 v[144:145], v[76:77]
	v_mov_b64_e32 v[146:147], v[78:79]
	v_pk_mul_f32 v[152:153], v[26:27], v[150:151] op_sel_hi:[1,0]
	v_pk_mul_f32 v[154:155], v[24:25], v[150:151] op_sel_hi:[1,0]
	s_nop 0
	v_mov_b32_dpp v222, v152 row_ror:1 row_mask:0xf bank_mask:0xf
	v_mov_b32_dpp v160, v154 row_ror:1 row_mask:0xf bank_mask:0xf
	v_mov_b32_dpp v195, v155 row_ror:1 row_mask:0xf bank_mask:0xf
	v_mov_b32_dpp v230, v153 row_ror:1 row_mask:0xf bank_mask:0xf
	v_mov_b32_dpp v194, v154 row_ror:2 row_mask:0xf bank_mask:0xf
	v_mov_b32_dpp v221, v155 row_ror:2 row_mask:0xf bank_mask:0xf
	v_mov_b32_dpp v223, v152 row_ror:2 row_mask:0xf bank_mask:0xf
	v_mov_b32_dpp v231, v153 row_ror:2 row_mask:0xf bank_mask:0xf
	v_cndmask_b32_e64 v183, v204, v195, s[14:15]
	v_cndmask_b32_e64 v182, v196, v160, s[68:69]
	v_cndmask_b32_e64 v191, v232, v230, s[14:15]
	v_cndmask_b32_e64 v190, v210, v222, s[68:69]
	v_cndmask_b32_e64 v187, v205, v221, s[64:65]
	v_cndmask_b32_e64 v186, v197, v194, s[66:67]
	v_cndmask_b32_e64 v189, v233, v231, s[64:65]
	v_cndmask_b32_e64 v188, v211, v223, s[66:67]
	v_pk_mul_f32 v[136:137], v[136:137], v[182:183]
	v_pk_mul_f32 v[138:139], v[138:139], v[190:191]
	v_pk_fma_f32 v[136:137], v[140:141], v[186:187], v[136:137]
	v_pk_fma_f32 v[138:139], v[142:143], v[188:189], v[138:139]
	v_pk_fma_f32 v[136:137], v[154:155], v[144:145], v[136:137]
	v_pk_fma_f32 v[138:139], v[152:153], v[146:147], v[138:139]
	v_mul_f32_e32 v140, 0xbfb8aa3b, v136
	v_mul_f32_e32 v141, 0xbfb8aa3b, v137
	v_mul_f32_e32 v142, 0xbfb8aa3b, v138
; #define PG8_LAS __attribute__((address_space(3)))
; __device__ __forceinline__ unsigned cvt_pk_bf16(float lo, float hi) { typedef float f2 __attribute__((ext_vector_type(2))); typedef __bf16 b2 __attribute__((ext_vector_type(2))); f2 v = {lo, hi}; b2 b = __builtin_convertvector(v, b2); return __builtin_bit_cast(unsigned, b); }
; template <int CTRL> __device__ __forceinline__ float dpp_ror(float v) { return __builtin_bit_cast(float, __builtin_amdgcn_mov_dpp(__builtin_bit_cast(int, v), CTRL, 0xf, 0xf, false)); }
;     __device__ __forceinline__ void operator()(f32x4 (&acc)[2][2][4][2], const Unit& u, int wr, int wc, int fr_in, int fq_in) const {
;     ...
;                 for (int n = 0; n < 2; ++n) { f32x4 p1, p2;
;                     if (m == 0) { const int sai = (wr == 1) ? ai : (ai > 0 ? ai - 1 : 0); const int swave = (wr ^ 1) * 4 + wc;
;                         p1 = *(const PG8_LAS f32x4*)(xl + ((((swave * 2 + sai) * 2 + 1) * 4 + fq) * 8) + 4 * n); p2 = *(const PG8_LAS f32x4*)(xl + ((((swave * 2 + sai) * 2 + (fr == 0 ? 0 : 1)) * 4 + fq) * 8) + 4 * n); }
; #pragma unroll
;                     for (int e = 0; e < 4; ++e) { const float gv = acc[ai][0][m][n][e]; const float s1 = dpp_ror<0x121>(gv), s2 = dpp_ror<0x122>(gv); float q1, q2;
;                         if (m > 0) { const float pvv = acc[ai][0][m > 0 ? m - 1 : 0][n][e]; q1 = dpp_ror<0x121>(pvv); q2 = dpp_ror<0x122>(pvv); } else { q1 = p1[e]; q2 = p2[e]; }
;                         p1[e] = fr >= 1 ? s1 : q1; p2[e] = fr >= 2 ? s2 : q2; }
;                     const f32x4 w0 = *(const f32x4*)(cw + cb + 4 * n), w1 = *(const f32x4*)(cw + 2816 + cb + 4 * n), w2 = *(const f32x4*)(cw + 2 * 2816 + cb + 4 * n);
;                     const f32x4 cv = w0 * p2 + w1 * p1 + w2 * acc[ai][0][m][n]; f32x4 o;
; #pragma unroll
;                     for (int e = 0; e < 4; ++e) o[e] = cv[e] * __builtin_amdgcn_rcpf(1.0f + __builtin_amdgcn_exp2f(-1.4426950408889634f * cv[e])) * acc[ai][1][m][n][e];
;                     typedef unsigned u32x2_ __attribute__((ext_vector_type(2))); u32x2_ wv; wv.x = cvt_pk_bf16(o[0], o[1]); wv.y = cvt_pk_bf16(o[2], o[3]);
;                     if (!skip) *(u32x2_*)(op + 4 * n) = wv;
;                     asm volatile("" ::: "memory"); } }
	v_mul_f32_e32 v143, 0xbfb8aa3b, v139
	v_exp_f32_e32 v140, v140
	v_exp_f32_e32 v141, v141
	v_exp_f32_e32 v142, v142
	v_exp_f32_e32 v143, v143
	v_add_f32_e32 v140, 1.0, v140
	v_add_f32_e32 v141, 1.0, v141
	v_add_f32_e32 v142, 1.0, v142
	v_add_f32_e32 v143, 1.0, v143
	v_rcp_f32_e32 v140, v140
	v_rcp_f32_e32 v141, v141
	v_rcp_f32_e32 v142, v142
	v_rcp_f32_e32 v143, v143
	v_pk_mul_f32 v[144:145], v[18:19], v[150:151] op_sel_hi:[1,0]
	v_pk_mul_f32 v[146:147], v[16:17], v[150:151] op_sel_hi:[1,0]
	v_pk_mul_f32 v[136:137], v[136:137], v[140:141]
	v_pk_mul_f32 v[138:139], v[138:139], v[142:143]
	v_pk_mul_f32 v[136:137], v[146:147], v[136:137]
	v_pk_mul_f32 v[138:139], v[144:145], v[138:139]
	v_cvt_pk_bf16_f32 v136, v136, v137
	v_cvt_pk_bf16_f32 v137, v138, v139
	v_mov_b64_e32 v[14:15], v[136:137]
	global_store_dwordx4 v[148:149], v[12:15], off
	v_mov_b64_e32 v[136:137], v[116:117]
	v_mov_b64_e32 v[138:139], v[118:119]
	v_mov_b64_e32 v[140:141], v[112:113]
	v_mov_b64_e32 v[142:143], v[114:115]
	v_mov_b64_e32 v[144:145], v[120:121]
	v_mov_b64_e32 v[146:147], v[122:123]
	v_mov_b32_dpp v154, v132 row_ror:1 row_mask:0xf bank_mask:0xf
	v_mov_b32_dpp v155, v133 row_ror:1 row_mask:0xf bank_mask:0xf
	v_mov_b32_dpp v188, v134 row_ror:1 row_mask:0xf bank_mask:0xf
	v_mov_b32_dpp v189, v135 row_ror:1 row_mask:0xf bank_mask:0xf
	v_mov_b32_dpp v182, v132 row_ror:2 row_mask:0xf bank_mask:0xf
	v_mov_b32_dpp v183, v133 row_ror:2 row_mask:0xf bank_mask:0xf
	v_mov_b32_dpp v186, v134 row_ror:2 row_mask:0xf bank_mask:0xf
	v_mov_b32_dpp v187, v135 row_ror:2 row_mask:0xf bank_mask:0xf
	v_cndmask_b32_e64 v155, v193, v155, s[14:15]
	v_cndmask_b32_e64 v154, v181, v154, s[68:69]
	v_cndmask_b32_e64 v189, v215, v189, s[14:15]
	v_cndmask_b32_e64 v188, v213, v188, s[68:69]
	v_cndmask_b32_e64 v183, v212, v183, s[64:65]
	v_cndmask_b32_e64 v182, v192, v182, s[66:67]
	v_cndmask_b32_e64 v187, v220, v187, s[64:65]
	v_cndmask_b32_e64 v186, v214, v186, s[66:67]
	v_mov_b32_e32 v148, v184
	v_mov_b32_e32 v149, v184
	v_pk_mul_f32 v[150:151], v[6:7], v[148:149]
	v_pk_mul_f32 v[152:153], v[4:5], v[184:185]
	v_pk_mul_f32 v[136:137], v[136:137], v[154:155]
	v_pk_mul_f32 v[138:139], v[138:139], v[188:189]
	v_pk_fma_f32 v[136:137], v[140:141], v[182:183], v[136:137]
	v_pk_fma_f32 v[138:139], v[142:143], v[186:187], v[138:139]
	v_pk_fma_f32 v[132:133], v[132:133], v[144:145], v[136:137]
	v_pk_fma_f32 v[134:135], v[134:135], v[146:147], v[138:139]
	v_mul_f32_e32 v136, 0xbfb8aa3b, v132
	v_mul_f32_e32 v137, 0xbfb8aa3b, v133
	v_mul_f32_e32 v138, 0xbfb8aa3b, v134
	v_mul_f32_e32 v139, 0xbfb8aa3b, v135
	v_exp_f32_e32 v136, v136
	v_exp_f32_e32 v137, v137
	v_exp_f32_e32 v138, v138
	v_exp_f32_e32 v139, v139
	v_add_f32_e32 v136, 1.0, v136
	v_add_f32_e32 v137, 1.0, v137
	v_add_f32_e32 v138, 1.0, v138
	v_add_f32_e32 v139, 1.0, v139
	v_rcp_f32_e32 v136, v136
	v_rcp_f32_e32 v137, v137
	v_rcp_f32_e32 v138, v138
	v_rcp_f32_e32 v139, v139
	v_mad_i64_i32 v[140:141], s[0:1], v180, s33, v[156:157]
	v_pk_mul_f32 v[132:133], v[132:133], v[136:137]
	v_pk_mul_f32 v[134:135], v[134:135], v[138:139]
	v_pk_mul_f32 v[132:133], v[152:153], v[132:133]
	v_pk_mul_f32 v[134:135], v[150:151], v[134:135]
	v_lshl_add_u64 v[144:145], v[140:141], 0, v[158:159]
	v_cvt_pk_bf16_f32 v132, v132, v133
	v_cvt_pk_bf16_f32 v133, v134, v135
	v_mov_b64_e32 v[12:13], v[132:133]
	v_mov_b64_e32 v[132:133], v[72:73]
	v_mov_b64_e32 v[134:135], v[74:75]
	v_mov_b64_e32 v[136:137], v[124:125]
	v_mov_b64_e32 v[138:139], v[126:127]
	v_mov_b64_e32 v[140:141], v[76:77]
	v_mov_b64_e32 v[142:143], v[78:79]
	v_mov_b32_dpp v146, v128 row_ror:1 row_mask:0xf bank_mask:0xf
	v_mov_b32_dpp v147, v129 row_ror:1 row_mask:0xf bank_mask:0xf
	v_mov_b32_dpp v154, v130 row_ror:1 row_mask:0xf bank_mask:0xf
	v_mov_b32_dpp v155, v131 row_ror:1 row_mask:0xf bank_mask:0xf
	v_mov_b32_dpp v150, v128 row_ror:2 row_mask:0xf bank_mask:0xf
	v_mov_b32_dpp v151, v129 row_ror:2 row_mask:0xf bank_mask:0xf
	v_mov_b32_dpp v152, v130 row_ror:2 row_mask:0xf bank_mask:0xf
	v_mov_b32_dpp v153, v131 row_ror:2 row_mask:0xf bank_mask:0xf
	v_cndmask_b32_e64 v147, v195, v147, s[14:15]
	v_cndmask_b32_e64 v146, v160, v146, s[68:69]
	v_cndmask_b32_e64 v155, v230, v155, s[14:15]
	v_cndmask_b32_e64 v154, v222, v154, s[68:69]
	v_cndmask_b32_e64 v151, v221, v151, s[64:65]
	v_cndmask_b32_e64 v150, v194, v150, s[66:67]
	v_cndmask_b32_e64 v153, v231, v153, s[64:65]
	v_cndmask_b32_e64 v152, v223, v152, s[66:67]
	s_mov_b64 s[0:1], 0
	v_pk_mul_f32 v[132:133], v[132:133], v[146:147]
	v_pk_mul_f32 v[134:135], v[134:135], v[154:155]
	v_pk_fma_f32 v[132:133], v[136:137], v[150:151], v[132:133]
	v_pk_fma_f32 v[134:135], v[138:139], v[152:153], v[134:135]
	v_pk_fma_f32 v[128:129], v[128:129], v[140:141], v[132:133]
	v_pk_fma_f32 v[130:131], v[130:131], v[142:143], v[134:135]
	v_mul_f32_e32 v132, 0xbfb8aa3b, v128
	v_mul_f32_e32 v133, 0xbfb8aa3b, v129
	v_mul_f32_e32 v134, 0xbfb8aa3b, v130
	v_mul_f32_e32 v135, 0xbfb8aa3b, v131
	v_exp_f32_e32 v132, v132
	v_exp_f32_e32 v133, v133
	v_exp_f32_e32 v134, v134
	v_exp_f32_e32 v135, v135
	v_add_f32_e32 v132, 1.0, v132
	v_add_f32_e32 v133, 1.0, v133
	v_add_f32_e32 v134, 1.0, v134
	v_add_f32_e32 v135, 1.0, v135
	v_rcp_f32_e32 v132, v132
	v_rcp_f32_e32 v133, v133
	v_rcp_f32_e32 v134, v134
	v_rcp_f32_e32 v135, v135
	v_pk_mul_f32 v[136:137], v[2:3], v[148:149]
	v_pk_mul_f32 v[138:139], v[0:1], v[184:185]
	v_pk_mul_f32 v[128:129], v[128:129], v[132:133]
	v_pk_mul_f32 v[130:131], v[130:131], v[134:135]
	v_pk_mul_f32 v[128:129], v[138:139], v[128:129]
	v_pk_mul_f32 v[130:131], v[136:137], v[130:131]
	v_cvt_pk_bf16_f32 v128, v128, v129
	v_cvt_pk_bf16_f32 v129, v130, v131
	v_mov_b64_e32 v[14:15], v[128:129]
	global_store_dwordx4 v[144:145], v[12:15], off
